# output pass: the chain waves compute their half of stage A (LoRA MFMA + sigmoid) for the next chunk right after their stage D while the other wave inverts; rate array in its own LDS image
# speedup vs baseline: 1.0281x; 1.0082x over previous
.LBB0_1107:
	s_and_b64 s[12:13], s[10:11], exec
	s_cselect_b32 s95, s93, s94
	v_mov_b32_e32 v141, v176
	s_cmp_lt_u32 s88, 7
	s_cselect_b64 s[58:59], -1, 0
	v_bfe_u32 v51, v141, 5, 1
	s_add_i32 s95, s95, s87
	v_and_b32_e32 v70, 31, v141
	v_lshlrev_b32_e32 v0, 4, v51
	v_or_b32_e32 v71, s84, v70
	s_cmp_eq_u32 s88, 0
	s_cbranch_scc1 .La_full_b
	s_cmp_lg_u64 s[8:9], 0
	s_cbranch_scc1 .La_skip_b
.La_full_b:
	s_waitcnt vmcnt(3)
	v_mfma_f32_32x32x16_bf16 v[34:49], v[98:101], v[82:85], 0
	v_mfma_f32_32x32x16_bf16 v[34:49], v[102:105], v[86:89], v[34:49]
	v_mfma_f32_32x32x16_bf16 v[34:49], v[106:109], v[90:93], v[34:49]
	v_mfma_f32_32x32x16_bf16 v[34:49], v[110:113], v[94:97], v[34:49]
	s_cmp_gt_u32 s88, 6
	s_cbranch_scc1 .LBB0_1109
	v_xor_b32_e32 v50, 31, v70
	v_cndmask_b32_e64 v50, v50, v70, s[10:11]
	v_or_b32_e32 v52, s95, v50
	v_ashrrev_i32_e32 v53, 31, v52
	v_lshlrev_b64 v[52:53], 8, v[52:53]
	v_lshl_add_u64 v[52:53], s[50:51], 0, v[52:53]
	v_lshl_add_u64 v[52:53], v[52:53], 0, v[0:1]
	global_load_dwordx4 v[98:101], v[52:53], off
	global_load_dwordx4 v[102:105], v[52:53], off offset:32
	global_load_dwordx4 v[106:109], v[52:53], off offset:64
	global_load_dwordx4 v[110:113], v[52:53], off offset:96
.LBB0_1109:
	s_mov_b64 s[12:13], -1
	s_andn2_b64 vcc, exec, s[8:9]
	s_nop 7
	v_add_f32_e32 v58, v157, v34
	v_mul_u32_u24_e32 v34, 0x410, v51
	v_add_f32_e32 v57, v157, v35
	v_add_f32_e32 v56, v157, v36
	v_add_f32_e32 v55, v157, v37
	v_add_f32_e32 v54, v157, v38
	v_add_f32_e32 v53, v157, v39
	v_add_f32_e32 v52, v157, v40
	v_add_f32_e32 v50, v157, v41
	v_add_f32_e32 v42, v157, v42
	v_add_f32_e32 v41, v157, v43
	v_add_f32_e32 v40, v157, v44
	v_add_f32_e32 v39, v157, v45
	v_add_f32_e32 v38, v157, v46
	v_add_f32_e32 v37, v157, v47
	v_add_f32_e32 v36, v157, v48
	v_add_f32_e32 v35, v157, v49
	s_cbranch_vccnz .LBB0_1111
	v_mul_f32_e32 v43, 0xbfb8aa3b, v58
	v_mul_f32_e32 v45, 0xbfb8aa3b, v57
	v_exp_f32_e32 v44, v43
	v_exp_f32_e32 v45, v45
	v_mul_f32_e32 v48, 0xbfb8aa3b, v56
	v_mul_f32_e32 v49, 0xbfb8aa3b, v55
	v_add_f32_e32 v44, 1.0, v44
	v_add_f32_e32 v45, 1.0, v45
	v_rcp_f32_e32 v44, v44
	v_rcp_f32_e32 v45, v45
	v_exp_f32_e32 v48, v48
	v_exp_f32_e32 v49, v49
	v_mul_u32_u24_e32 v43, 0x410, v51
	v_lshl_add_u32 v46, v71, 2, v43
	v_add_u32_e32 v46, 0xd180, v46
	v_add_u32_e32 v47, 0x2000, v46
	ds_write2_b32 v47, v44, v45 offset0:32 offset1:97
	v_add_f32_e32 v44, 1.0, v48
	v_add_f32_e32 v45, 1.0, v49
	v_mul_f32_e32 v48, 0xbfb8aa3b, v54
	v_mul_f32_e32 v49, 0xbfb8aa3b, v53
	v_rcp_f32_e32 v44, v44
	v_rcp_f32_e32 v45, v45
	v_exp_f32_e32 v48, v48
	v_exp_f32_e32 v49, v49
	s_mov_b64 s[12:13], 0
	ds_write2_b32 v47, v44, v45 offset0:162 offset1:227
	v_add_f32_e32 v44, 1.0, v48
	v_add_f32_e32 v45, 1.0, v49
	v_mul_f32_e32 v48, 0xbfb8aa3b, v52
	v_mul_f32_e32 v49, 0xbfb8aa3b, v50
	v_rcp_f32_e32 v44, v44
	v_rcp_f32_e32 v45, v45
	v_exp_f32_e32 v48, v48
	v_exp_f32_e32 v49, v49
	v_add_u32_e32 v47, 0x2800, v46
	ds_write2_b32 v47, v44, v45 offset0:40 offset1:105
	v_add_f32_e32 v44, 1.0, v48
	v_add_f32_e32 v45, 1.0, v49
	v_mul_f32_e32 v48, 0xbfb8aa3b, v42
	v_mul_f32_e32 v49, 0xbfb8aa3b, v41
	v_rcp_f32_e32 v44, v44
	v_rcp_f32_e32 v45, v45
	v_exp_f32_e32 v48, v48
	v_exp_f32_e32 v49, v49
	ds_write2_b32 v47, v44, v45 offset0:170 offset1:235
	v_add_f32_e32 v44, 1.0, v48
	v_add_f32_e32 v45, 1.0, v49
	v_mul_f32_e32 v48, 0xbfb8aa3b, v40
	v_mul_f32_e32 v49, 0xbfb8aa3b, v39
	v_rcp_f32_e32 v44, v44
	v_rcp_f32_e32 v45, v45
	v_exp_f32_e32 v48, v48
	v_exp_f32_e32 v49, v49
	v_add_u32_e32 v47, 0x3000, v46
	ds_write2_b32 v47, v44, v45 offset0:48 offset1:113
	v_add_f32_e32 v44, 1.0, v48
	v_add_f32_e32 v45, 1.0, v49
	v_mul_f32_e32 v48, 0xbfb8aa3b, v38
	v_rcp_f32_e32 v44, v44
	v_rcp_f32_e32 v45, v45
	v_exp_f32_e32 v48, v48
	v_mul_f32_e32 v49, 0xbfb8aa3b, v37
	v_exp_f32_e32 v49, v49
	ds_write2_b32 v47, v44, v45 offset0:178 offset1:243
	v_add_f32_e32 v44, 1.0, v48
	v_rcp_f32_e32 v45, v44
	v_add_f32_e32 v44, 1.0, v49
	v_rcp_f32_e32 v47, v44
	v_mul_f32_e32 v44, 0xbfb8aa3b, v36
	v_exp_f32_e32 v44, v44
	v_mul_f32_e32 v48, 0xbfb8aa3b, v35
	v_exp_f32_e32 v48, v48
	v_add_u32_e32 v49, 0x3800, v46
	v_add_f32_e32 v44, 1.0, v44
	v_rcp_f32_e32 v59, v44
	v_add_f32_e32 v44, 1.0, v48
	v_rcp_f32_e32 v44, v44
	ds_write2_b32 v49, v45, v47 offset0:56 offset1:121
	ds_write_b32 v46, v59 offset:15080
	.LBB0_1111:
	s_andn2_b64 vcc, exec, s[12:13]
	s_mov_b32 s12, 0xf200
	s_cbranch_vccnz .LBB0_1113
	v_mul_f32_e32 v43, 0xbfb8aa3b, v58
	v_exp_f32_e32 v43, v43
	v_mul_f32_e32 v44, 0xbfb8aa3b, v57
	v_mul_f32_e32 v45, 0xbfb8aa3b, v56
	v_exp_f32_e32 v46, v44
	v_exp_f32_e32 v45, v45
	v_add_f32_e32 v43, 1.0, v43
	v_rcp_f32_e32 v44, v43
	v_add_f32_e32 v43, 1.0, v46
	v_rcp_f32_e32 v46, v43
	v_add_f32_e32 v43, 1.0, v45
	v_mul_f32_e32 v45, 0xbfb8aa3b, v55
	v_exp_f32_e32 v47, v45
	v_mul_f32_e32 v45, 0xbfb8aa3b, v54
	v_mul_f32_e32 v40, 0xbfb8aa3b, v40
	v_exp_f32_e32 v48, v45
	v_exp_f32_e32 v40, v40
	v_rcp_f32_e32 v45, v43
	v_add_f32_e32 v43, 1.0, v47
	v_rcp_f32_e32 v47, v43
	v_add_f32_e32 v43, 1.0, v48
	v_mul_f32_e32 v48, 0xbfb8aa3b, v53
	v_add_f32_e32 v40, 1.0, v40
	v_mul_f32_e32 v39, 0xbfb8aa3b, v39
	v_exp_f32_e32 v49, v48
	v_rcp_f32_e32 v61, v40
	v_exp_f32_e32 v40, v39
	v_mul_f32_e32 v48, 0xbfb8aa3b, v52
	v_mul_f32_e32 v42, 0xbfb8aa3b, v42
	v_mul_f32_e32 v38, 0xbfb8aa3b, v38
	v_exp_f32_e32 v53, v48
	v_rcp_f32_e32 v48, v43
	v_add_f32_e32 v43, 1.0, v49
	v_mul_f32_e32 v49, 0xbfb8aa3b, v50
	v_exp_f32_e32 v42, v42
	v_add_f32_e32 v40, 1.0, v40
	v_exp_f32_e32 v38, v38
	v_mul_f32_e32 v37, 0xbfb8aa3b, v37
	v_mul_f32_e32 v35, 0xbfb8aa3b, v35
	v_exp_f32_e32 v50, v49
	v_rcp_f32_e32 v63, v40
	v_exp_f32_e32 v40, v37
	v_mul_f32_e32 v36, 0xbfb8aa3b, v36
	v_exp_f32_e32 v35, v35
	v_exp_f32_e32 v36, v36
	v_rcp_f32_e32 v52, v43
	v_add_f32_e32 v43, 1.0, v53
	v_add_f32_e32 v42, 1.0, v42
	v_add_f32_e32 v38, 1.0, v38
	v_rcp_f32_e32 v49, v43
	v_add_f32_e32 v43, 1.0, v50
	v_rcp_f32_e32 v50, v42
	v_rcp_f32_e32 v42, v38
	v_add_f32_e32 v38, 1.0, v40
	v_add_f32_e32 v35, 1.0, v35
	v_cmp_lt_i32_e32 vcc, v153, v154
	v_pk_mul_f32 v[46:47], v[46:47], s[42:43] op_sel_hi:[1,0]
	v_rcp_f32_e32 v54, v38
	v_add_f32_e32 v36, 1.0, v36
	v_rcp_f32_e32 v55, v35
	v_cndmask_b32_e32 v35, v152, v153, vcc
	v_pk_mul_f32 v[56:57], v[44:45], s[42:43] op_sel_hi:[1,0]
	v_pk_fma_f32 v[44:45], v[44:45], s[42:43], v[46:47] op_sel_hi:[1,0,1]
	v_rcp_f32_e32 v53, v43
	v_rcp_f32_e32 v43, v36
	v_lshlrev_b32_e32 v35, 2, v35
	v_add_f32_e32 v36, v44, v45
	v_mul_f32_e32 v41, 0xbfb8aa3b, v41
	ds_bpermute_b32 v40, v35, v36
	v_exp_f32_e32 v41, v41
	v_pk_mul_f32 v[54:55], v[54:55], s[42:43] op_sel_hi:[1,0]
	v_pk_mul_f32 v[52:53], v[52:53], s[42:43] op_sel_hi:[1,0]
	v_pk_mul_f32 v[58:59], v[42:43], s[42:43] op_sel_hi:[1,0]
	v_pk_fma_f32 v[42:43], v[42:43], s[42:43], v[54:55] op_sel_hi:[1,0,1]
	v_pk_mul_f32 v[44:45], v[48:49], s[42:43] op_sel_hi:[1,0]
	v_pk_fma_f32 v[48:49], v[48:49], s[42:43], v[52:53] op_sel_hi:[1,0,1]
	v_pk_add_f32 v[42:43], v[42:43], v[42:43] op_sel:[0,1] op_sel_hi:[1,0]
	v_add_f32_e32 v41, 1.0, v41
	v_pk_add_f32 v[48:49], v[48:49], v[48:49] op_sel:[0,1] op_sel_hi:[1,0]
	s_waitcnt lgkmcnt(0)
	v_add_f32_e32 v43, 0, v40
	v_cmp_eq_u32_e32 vcc, 0, v51
	v_rcp_f32_e32 v60, v41
	ds_bpermute_b32 v38, v35, v48
	v_cndmask_b32_e64 v43, v43, 0, vcc
	v_add_f32_e32 v43, v56, v43
	v_lshl_add_u32 v56, v71, 2, v34
	v_add_f32_e32 v46, v46, v43
	v_mul_f32_e32 v62, 0xbf1b459e, v50
	ds_write2_b32 v56, v43, v46 offset1:65
	v_add_f32_e32 v43, v57, v46
	v_mul_f32_e32 v39, 0xbf1b459e, v60
	v_mul_f32_e32 v41, 0xbf1b459e, v61
	v_mul_f32_e32 v37, 0xbf1b459e, v63
	v_add_f32_e32 v46, v47, v43
	v_add_f32_e32 v40, v36, v40
	v_mov_b32_e32 v36, v1
	v_mov_b32_e32 v49, v62
	ds_write2_b32 v56, v43, v46 offset0:130 offset1:195
	s_waitcnt lgkmcnt(2)
	v_cndmask_b32_e64 v43, v38, 0, vcc
	v_pk_add_f32 v[36:37], v[40:41], v[36:37]
	v_pk_add_f32 v[38:39], v[48:49], v[38:39]
	ds_bpermute_b32 v42, v35, v42
	v_pk_add_f32 v[38:39], v[38:39], v[36:37]
	ds_bpermute_b32 v35, v35, v39
	v_add_f32_e32 v36, v36, v43
	v_add_f32_e32 v36, v44, v36
	v_add_f32_e32 v37, v52, v36
	v_add_u32_e32 v40, 0x800, v56
	ds_write2_b32 v40, v36, v37 offset0:8 offset1:73
	v_add_f32_e32 v36, v45, v37
	v_add_f32_e32 v37, v53, v36
	ds_write2_b32 v40, v36, v37 offset0:138 offset1:203
	s_waitcnt lgkmcnt(2)
	v_cndmask_b32_e64 v36, v35, 0, vcc
	v_add_f32_e32 v36, v38, v36
	v_fmac_f32_e32 v36, 0xbf1b459e, v50
	v_fmamk_f32 v37, v60, 0xbf1b459e, v36
	v_add_u32_e32 v40, 0x1000, v56
	ds_write2_b32 v40, v36, v37 offset0:16 offset1:81
	v_fmac_f32_e32 v37, 0xbf1b459e, v61
	v_fmamk_f32 v36, v63, 0xbf1b459e, v37
	v_add_f32_e32 v35, v39, v35
	ds_write2_b32 v40, v37, v36 offset0:146 offset1:211
	v_add_f32_e32 v35, v38, v35
	v_cndmask_b32_e64 v36, v42, 0, vcc
	v_add_f32_e32 v35, v35, v36
	v_add_f32_e32 v35, v58, v35
	v_add_f32_e32 v36, v54, v35
	v_add_u32_e32 v37, 0x1800, v56
	ds_write2_b32 v37, v35, v36 offset0:24 offset1:89
	v_add_f32_e32 v35, v59, v36
	s_mov_b32 s12, 0
	v_add_f32_e32 v44, v55, v35
	v_mov_b32_e32 v43, v34
	ds_write_b32 v56, v35 offset:6760
	.LBB0_1113:
	v_lshlrev_b32_e32 v144, 2, v71
	v_add3_u32 v34, s12, v144, v43
	v_and_b32_e32 v73, 7, v141
	ds_write_b32 v34, v44 offset:7020
	s_branch .La_join_b
.La_skip_b:
	v_lshlrev_b32_e32 v144, 2, v71
	v_and_b32_e32 v73, 7, v141
.La_join_b:
	s_waitcnt lgkmcnt(0)
	s_barrier
	s_waitcnt vmcnt(0)
	v_lshrrev_b32_e32 v72, 3, v141
	v_lshlrev_b32_e32 v50, 5, v73
	v_mul_u32_u24_e32 v161, 0x104, v72
	v_cmp_lt_u32_e32 vcc, 0, v72
	v_add_u32_e32 v68, v161, v50
	v_mov_b32_e32 v162, 0x104
	v_add_u32_e32 v69, 0xf200, v68
	ds_read_b128 v[214:217], v50 offset:61120
	ds_read_b128 v[218:221], v50 offset:61136
	ds_read2_b32 v[34:35], v69 offset0:0 offset1:1
	ds_read2_b32 v[36:37], v69 offset0:2 offset1:3
	ds_read2_b32 v[38:39], v69 offset0:4 offset1:5
	ds_read2_b32 v[40:41], v69 offset0:6 offset1:7
	ds_read_b128 v[42:45], v50 offset:61376
	ds_read_b128 v[46:49], v50 offset:61392
	ds_read2_b32 v[60:61], v68 offset0:0 offset1:1
	ds_read2_b32 v[62:63], v68 offset0:2 offset1:3
	ds_read2_b32 v[64:65], v68 offset0:4 offset1:5
	ds_read2_b32 v[66:67], v68 offset0:6 offset1:7
	v_mov_b32_e32 v230, 0x3fb8aa3b
	v_mov_b32_e32 v231, 0x3fb8aa3b
	v_cndmask_b32_e32 v162, 0, v162, vcc
	v_cndmask_b32_e32 v143, 0, v230, vcc
	v_mov_b32_e32 v232, 1.0
	v_mov_b32_e32 v233, 1.0
	v_sub_u32_e32 v145, v68, v162
	v_add_u32_e32 v158, 0x1f7c, v50
	v_mul_u32_u24_e32 v159, 0x280, v73
	v_lshrrev_b32_e32 v161, 3, v72
	v_and_b32_e32 v163, 4, v73
	v_xor_b32_e32 v161, v161, v73
	v_lshl_add_u32 v159, v163, 4, v159
	v_and_b32_e32 v161, 3, v161
	v_and_b32_e32 v163, 7, v72
	v_lshl_add_u32 v159, v161, 4, v159
	v_mul_u32_u24_e32 v160, 0x90, v72
	v_lshl_add_u32 v159, v163, 1, v159
	v_lshl_add_u32 v160, v73, 4, v160
	v_lshlrev_b32_e32 v222, 16, v122
	v_and_b32_e32 v223, 0xffff0000, v122
	v_lshlrev_b32_e32 v224, 16, v123
	v_and_b32_e32 v225, 0xffff0000, v123
	v_lshlrev_b32_e32 v226, 16, v124
	v_and_b32_e32 v227, 0xffff0000, v124
	v_lshlrev_b32_e32 v228, 16, v125
	v_and_b32_e32 v229, 0xffff0000, v125
	s_waitcnt lgkmcnt(0)
	ds_read2_b32 v[74:75], v158 offset0:0 offset1:1
	ds_read2_b32 v[76:77], v158 offset0:2 offset1:3
	ds_read2_b32 v[78:79], v158 offset0:4 offset1:5
	ds_read2_b32 v[80:81], v158 offset0:6 offset1:7
	ds_read2_b32 v[126:127], v145 offset0:0 offset1:1
	ds_read2_b32 v[128:129], v145 offset0:2 offset1:3
	ds_read2_b32 v[130:131], v145 offset0:4 offset1:5
	ds_read2_b32 v[132:133], v145 offset0:6 offset1:7
	v_pk_mul_f32 v[214:215], v[214:215], v[222:223]
	v_pk_mul_f32 v[216:217], v[216:217], v[224:225]
	v_pk_mul_f32 v[218:219], v[218:219], v[226:227]
	v_pk_mul_f32 v[220:221], v[220:221], v[228:229]
	v_pk_mul_f32 v[234:235], v[214:215], v[214:215]
	v_pk_fma_f32 v[234:235], v[216:217], v[216:217], v[234:235]
	v_pk_fma_f32 v[234:235], v[218:219], v[218:219], v[234:235]
	v_pk_fma_f32 v[234:235], v[220:221], v[220:221], v[234:235]
	v_pk_add_f32 v[52:53], v[34:35], v[232:233] neg_lo:[0,1] neg_hi:[0,1]
	v_pk_add_f32 v[54:55], v[36:37], v[232:233] neg_lo:[0,1] neg_hi:[0,1]
	v_pk_add_f32 v[56:57], v[38:39], v[232:233] neg_lo:[0,1] neg_hi:[0,1]
	v_pk_add_f32 v[58:59], v[40:41], v[232:233] neg_lo:[0,1] neg_hi:[0,1]
	v_add_f32_e32 v234, v234, v235
	v_pk_fma_f32 v[42:43], v[52:53], v[42:43], v[232:233]
	v_pk_fma_f32 v[44:45], v[54:55], v[44:45], v[232:233]
	v_add_f32_dpp v234, v234, v234 quad_perm:[1,0,3,2] row_mask:0xf bank_mask:0xf bound_ctrl:1
	v_pk_fma_f32 v[46:47], v[56:57], v[46:47], v[232:233]
	v_pk_fma_f32 v[48:49], v[58:59], v[48:49], v[232:233]
	v_add_f32_dpp v234, v234, v234 quad_perm:[2,3,0,1] row_mask:0xf bank_mask:0xf bound_ctrl:1
	v_pk_mul_f32 v[222:223], v[222:223], v[42:43]
	v_pk_mul_f32 v[224:225], v[224:225], v[44:45]
	v_mov_b32_dpp v235, v234 row_half_mirror row_mask:0xf bank_mask:0xf bound_ctrl:1
	v_pk_mul_f32 v[226:227], v[226:227], v[46:47]
	v_pk_mul_f32 v[228:229], v[228:229], v[48:49]
	ds_read_b128 v[42:45], v50 offset:61632
	ds_read_b128 v[46:49], v50 offset:61648
	v_add_f32_e32 v234, v234, v235
	v_add_f32_e32 v234, 0x2b8cbccc, v234
	v_rsq_f32_e32 v234, v234
	s_waitcnt lgkmcnt(2)
	v_pk_mul_f32 v[214:215], v[214:215], v[234:235] op_sel_hi:[1,0]
	v_pk_mul_f32 v[216:217], v[216:217], v[234:235] op_sel_hi:[1,0]
	v_pk_mul_f32 v[218:219], v[218:219], v[234:235] op_sel_hi:[1,0]
	v_pk_mul_f32 v[220:221], v[220:221], v[234:235] op_sel_hi:[1,0]
	v_cmp_eq_u32_e32 vcc, 31, v72
	v_pk_mul_f32 v[52:53], v[214:215], v[34:35]
	v_pk_mul_f32 v[54:55], v[216:217], v[36:37]
	v_pk_mul_f32 v[56:57], v[218:219], v[38:39]
	v_pk_mul_f32 v[58:59], v[220:221], v[40:41]
	s_and_saveexec_b64 s[60:61], vcc
	s_cbranch_execz .Lc_nogc_b
	v_pk_mul_f32 v[34:35], v[74:75], v[230:231]
	v_pk_mul_f32 v[36:37], v[76:77], v[230:231]
	v_pk_mul_f32 v[38:39], v[78:79], v[230:231]
	v_pk_mul_f32 v[40:41], v[80:81], v[230:231]
	v_exp_f32_e64 v34, v34
	v_exp_f32_e64 v35, v35
	v_exp_f32_e64 v36, v36
	v_exp_f32_e64 v37, v37
	v_exp_f32_e64 v38, v38
	v_exp_f32_e64 v39, v39
	v_exp_f32_e64 v40, v40
	v_exp_f32_e64 v41, v41
	ds_write_b128 v50, v[34:37] offset:60864
	ds_write_b128 v50, v[38:41] offset:60880

.Le23_skip_b:
		s_cmp_eq_u64 s[8:9], 0
		s_cbranch_scc1 .Lal_skip_b
		s_cmp_gt_u32 s88, 6
		s_cbranch_scc1 .Lal_skip_b
		s_cmp_lg_u64 s[10:11], 0
		s_cbranch_scc1 .Lal_w0_b
		s_waitcnt vmcnt(16)
		s_branch .Lal_w1_b
.Lal_w0_b:
		s_waitcnt vmcnt(0)
.Lal_w1_b:
		v_mfma_f32_32x32x16_bf16 v[34:49], v[98:101], v[82:85], 0
		v_mfma_f32_32x32x16_bf16 v[34:49], v[102:105], v[86:89], v[34:49]
		v_mfma_f32_32x32x16_bf16 v[34:49], v[106:109], v[90:93], v[34:49]
		v_mfma_f32_32x32x16_bf16 v[34:49], v[110:113], v[94:97], v[34:49]
		s_cmp_gt_u32 s88, 5
		s_cbranch_scc1 .Lal_np_b
		s_add_i32 s12, s93, 32
		s_sub_i32 s13, s94, 32
		s_cmp_lg_u64 s[10:11], 0
		s_cselect_b32 s12, s12, s13
		s_add_i32 s12, s12, s87
		v_lshlrev_b32_e32 v60, 4, v51
		v_mov_b32_e32 v61, 0
		v_xor_b32_e32 v50, 31, v70
		v_cndmask_b32_e64 v50, v50, v70, s[10:11]
		v_or_b32_e32 v52, s12, v50
		v_ashrrev_i32_e32 v53, 31, v52
		v_lshlrev_b64 v[52:53], 8, v[52:53]
		v_lshl_add_u64 v[52:53], s[50:51], 0, v[52:53]
		v_lshl_add_u64 v[52:53], v[52:53], 0, v[60:61]
		global_load_dwordx4 v[98:101], v[52:53], off
		global_load_dwordx4 v[102:105], v[52:53], off offset:32
		global_load_dwordx4 v[106:109], v[52:53], off offset:64
		global_load_dwordx4 v[110:113], v[52:53], off offset:96
.Lal_np_b:
		s_nop 7
		s_nop 3
		v_add_f32_e32 v58, v157, v34
		v_mul_u32_u24_e32 v34, 0x410, v51
		v_add_f32_e32 v57, v157, v35
		v_add_f32_e32 v56, v157, v36
		v_add_f32_e32 v55, v157, v37
		v_add_f32_e32 v54, v157, v38
		v_add_f32_e32 v53, v157, v39
		v_add_f32_e32 v52, v157, v40
		v_add_f32_e32 v50, v157, v41
		v_add_f32_e32 v42, v157, v42
		v_add_f32_e32 v41, v157, v43
		v_add_f32_e32 v40, v157, v44
		v_add_f32_e32 v39, v157, v45
		v_add_f32_e32 v38, v157, v46
		v_add_f32_e32 v37, v157, v47
		v_add_f32_e32 v36, v157, v48
		v_add_f32_e32 v35, v157, v49
		v_mul_f32_e32 v43, 0xbfb8aa3b, v58
		v_mul_f32_e32 v45, 0xbfb8aa3b, v57
		v_exp_f32_e32 v44, v43
		v_exp_f32_e32 v45, v45
		v_mul_f32_e32 v48, 0xbfb8aa3b, v56
		v_mul_f32_e32 v49, 0xbfb8aa3b, v55
		v_add_f32_e32 v44, 1.0, v44
		v_add_f32_e32 v45, 1.0, v45
		v_rcp_f32_e32 v44, v44
		v_rcp_f32_e32 v45, v45
		v_exp_f32_e32 v48, v48
		v_exp_f32_e32 v49, v49
		v_mul_u32_u24_e32 v43, 0x410, v51
		v_lshl_add_u32 v46, v71, 2, v43
		v_add_u32_e32 v46, 0xd180, v46
		v_add_u32_e32 v47, 0x2000, v46
		ds_write2_b32 v47, v44, v45 offset0:32 offset1:97
		v_add_f32_e32 v44, 1.0, v48
		v_add_f32_e32 v45, 1.0, v49
		v_mul_f32_e32 v48, 0xbfb8aa3b, v54
		v_mul_f32_e32 v49, 0xbfb8aa3b, v53
		v_rcp_f32_e32 v44, v44
		v_rcp_f32_e32 v45, v45
		v_exp_f32_e32 v48, v48
		v_exp_f32_e32 v49, v49
		ds_write2_b32 v47, v44, v45 offset0:162 offset1:227
		v_add_f32_e32 v44, 1.0, v48
		v_add_f32_e32 v45, 1.0, v49
		v_mul_f32_e32 v48, 0xbfb8aa3b, v52
		v_mul_f32_e32 v49, 0xbfb8aa3b, v50
		v_rcp_f32_e32 v44, v44
		v_rcp_f32_e32 v45, v45
		v_exp_f32_e32 v48, v48
		v_exp_f32_e32 v49, v49
		v_add_u32_e32 v47, 0x2800, v46
		ds_write2_b32 v47, v44, v45 offset0:40 offset1:105
		v_add_f32_e32 v44, 1.0, v48
		v_add_f32_e32 v45, 1.0, v49
		v_mul_f32_e32 v48, 0xbfb8aa3b, v42
		v_mul_f32_e32 v49, 0xbfb8aa3b, v41
		v_rcp_f32_e32 v44, v44
		v_rcp_f32_e32 v45, v45
		v_exp_f32_e32 v48, v48
		v_exp_f32_e32 v49, v49
		ds_write2_b32 v47, v44, v45 offset0:170 offset1:235
		v_add_f32_e32 v44, 1.0, v48
		v_add_f32_e32 v45, 1.0, v49
		v_mul_f32_e32 v48, 0xbfb8aa3b, v40
		v_mul_f32_e32 v49, 0xbfb8aa3b, v39
		v_rcp_f32_e32 v44, v44
		v_rcp_f32_e32 v45, v45
		v_exp_f32_e32 v48, v48
		v_exp_f32_e32 v49, v49
		v_add_u32_e32 v47, 0x3000, v46
		ds_write2_b32 v47, v44, v45 offset0:48 offset1:113
		v_add_f32_e32 v44, 1.0, v48
		v_add_f32_e32 v45, 1.0, v49
		v_mul_f32_e32 v48, 0xbfb8aa3b, v38
		v_rcp_f32_e32 v44, v44
		v_rcp_f32_e32 v45, v45
		v_exp_f32_e32 v48, v48
		v_mul_f32_e32 v49, 0xbfb8aa3b, v37
		v_exp_f32_e32 v49, v49
		ds_write2_b32 v47, v44, v45 offset0:178 offset1:243
		v_add_f32_e32 v44, 1.0, v48
		v_rcp_f32_e32 v45, v44
		v_add_f32_e32 v44, 1.0, v49
		v_rcp_f32_e32 v47, v44
		v_mul_f32_e32 v44, 0xbfb8aa3b, v36
		v_exp_f32_e32 v44, v44
		v_mul_f32_e32 v48, 0xbfb8aa3b, v35
		v_exp_f32_e32 v48, v48
		v_add_u32_e32 v49, 0x3800, v46
		v_add_f32_e32 v44, 1.0, v44
		v_rcp_f32_e32 v59, v44
		v_add_f32_e32 v44, 1.0, v48
		v_rcp_f32_e32 v44, v44
		ds_write2_b32 v49, v45, v47 offset0:56 offset1:121
		ds_write_b32 v46, v59 offset:15080
		v_mov_b32_e32 v60, 0xf200
		v_add3_u32 v34, v60, v144, v43
		ds_write_b32 v34, v44 offset:7020

.LBB0_1236:
	s_add_i32 s90, s91, 32
	s_and_b64 s[12:13], s[10:11], exec
	s_cselect_b32 s92, s90, s89
	v_mov_b32_e32 v141, v176
	s_cmp_lt_u32 s84, 15
	s_cselect_b64 s[58:59], -1, 0
	v_bfe_u32 v51, v141, 5, 1
	s_add_i32 s92, s92, s83
	v_and_b32_e32 v70, 31, v141
	v_lshlrev_b32_e32 v0, 4, v51
	v_or_b32_e32 v71, s82, v70
	s_cmp_eq_u32 s84, 0
	s_cbranch_scc1 .La_full_c
	s_cmp_lg_u64 s[8:9], 0
	s_cbranch_scc1 .La_skip_c
.La_full_c:
	s_waitcnt vmcnt(3)
	v_mfma_f32_32x32x16_bf16 v[34:49], v[98:101], v[82:85], 0
	v_mfma_f32_32x32x16_bf16 v[34:49], v[102:105], v[86:89], v[34:49]
	v_mfma_f32_32x32x16_bf16 v[34:49], v[106:109], v[90:93], v[34:49]
	v_mfma_f32_32x32x16_bf16 v[34:49], v[110:113], v[94:97], v[34:49]
	s_cmp_gt_u32 s84, 14
	s_cbranch_scc1 .LBB0_1238
	v_xor_b32_e32 v50, 31, v70
	v_cndmask_b32_e64 v50, v50, v70, s[10:11]
	v_or_b32_e32 v52, s92, v50
	v_ashrrev_i32_e32 v53, 31, v52
	v_lshlrev_b64 v[52:53], 8, v[52:53]
	v_lshl_add_u64 v[52:53], s[50:51], 0, v[52:53]
	v_lshl_add_u64 v[52:53], v[52:53], 0, v[0:1]
	global_load_dwordx4 v[98:101], v[52:53], off
	global_load_dwordx4 v[102:105], v[52:53], off offset:32
	global_load_dwordx4 v[106:109], v[52:53], off offset:64
	global_load_dwordx4 v[110:113], v[52:53], off offset:96

.Le23_skip_c:
		s_cmp_eq_u64 s[8:9], 0
		s_cbranch_scc1 .Lal_skip_c
		s_cmp_gt_u32 s84, 14
		s_cbranch_scc1 .Lal_skip_c
		s_cmp_lg_u64 s[10:11], 0
		s_cbranch_scc1 .Lal_w0_c
		s_waitcnt vmcnt(16)
		s_branch .Lal_w1_c

.Lal_w1_c:
		v_mfma_f32_32x32x16_bf16 v[34:49], v[98:101], v[82:85], 0
		v_mfma_f32_32x32x16_bf16 v[34:49], v[102:105], v[86:89], v[34:49]
		v_mfma_f32_32x32x16_bf16 v[34:49], v[106:109], v[90:93], v[34:49]
		v_mfma_f32_32x32x16_bf16 v[34:49], v[110:113], v[94:97], v[34:49]
		s_cmp_gt_u32 s84, 13
		s_cbranch_scc1 .Lal_np_c
		s_add_i32 s12, s91, 64
		s_sub_i32 s13, s89, 32
		s_cmp_lg_u64 s[10:11], 0
		s_cselect_b32 s12, s12, s13
		s_add_i32 s12, s12, s83
		v_lshlrev_b32_e32 v60, 4, v51
		v_mov_b32_e32 v61, 0
		v_xor_b32_e32 v50, 31, v70
		v_cndmask_b32_e64 v50, v50, v70, s[10:11]
		v_or_b32_e32 v52, s12, v50
		v_ashrrev_i32_e32 v53, 31, v52
		v_lshlrev_b64 v[52:53], 8, v[52:53]
		v_lshl_add_u64 v[52:53], s[50:51], 0, v[52:53]
		v_lshl_add_u64 v[52:53], v[52:53], 0, v[60:61]
		global_load_dwordx4 v[98:101], v[52:53], off
		global_load_dwordx4 v[102:105], v[52:53], off offset:32
		global_load_dwordx4 v[106:109], v[52:53], off offset:64
		global_load_dwordx4 v[110:113], v[52:53], off offset:96
